# v18: v17 + layer-0 W1OUT/WIN/WG/UB conversion also moved out of P0 into the idle CUs of the FFN1 last round
# baseline (speedup 1.0000x reference)
; __device__ __forceinline__ void phase_prologue(PtrTab TB, unsigned char* ws, float* xout, int l, LAS unsigned char* lds, int gw, int NGW, int lane, int wave) {
;     ...
;     for (int it = gw; it < S14; it += NGW) {
.LBB0_23:
	s_cmpk_eq_u32 s8, 0x800
	s_cbranch_scc0 .Ltr_plain
	s_cmpk_eq_u32 s94, 1
	s_cbranch_scc1 .LBB0_214
	s_mov_b32 s0, s71
	s_cmpk_lt_u32 s71, 1408
	s_cbranch_scc1 .Ltr_go
	s_addk_i32 s0, 2752
	s_branch .Ltr_go

; #define g1 (tab_in(TB, 2) + l * D)
; #define gm (tab_in(TB, 5) + l * D)
; __device__ __forceinline__ void phase_prologue(PtrTab TB, unsigned char* ws, float* xout, int l, LAS unsigned char* lds, int gw, int NGW, int lane, int wave) {
;     ...
;     for (int it = gw; it < S14; it += NGW) {
;         if (it < S1 || (it >= S12 && it < S13)) {
;             const bool second = it >= S12; const int r = second ? it - S12 : it; const int kb = r / 88, nb = r % 88; const int n = nb * 64;
;             const int half = n >= DFF ? 1 : 0, nn = n - half * DFF; const int drow = (nn >> 7) * 256 + half * 128 + (nn & 127);
;             tr_item(second ? w2i : w1i, 2 * DFF, n, kb * 64, second ? g2 : g1, (bf16*)(ws + (second ? WS_W2IN : WS_W1IN)), D, drow, scr, lane);
;         } else if (it < S2 || it >= S13) {
;             const bool second = it >= S13; const int r = second ? it - S13 : it - S1; const int kb = r / 16, nb = r % 16;
;             tr_item(second ? w2o : w1o, D, nb * 64, kb * 64, nullptr, (bf16*)(ws + (second ? WS_W2OUT : WS_W1OUT)), DFF, nb * 64, scr, lane);
;         } else if (it < S3) { const int r = it - S2, kb = r / 64, nb = r % 64; tr_item(win, INW, nb * 64, kb * 64, gm, (bf16*)(ws + WS_WIN), D, nb * 64, scr, lane);
;         } else if (it < S4) { const int r = it - S3, kb = r / 48, nb = r % 48; tr_item(win, INW, 4104 + nb * 64, kb * 64, gm, (bf16*)(ws + WS_WG), D, nb * 64, scr, lane);
;         } else if (it < S5) { const int r = it - S4, kb = r / 16, nb = r % 16; tr_item(wub, D, nb * 64, kb * 64, nullptr, (bf16*)(ws + WS_UB), D, nb * 64, scr, lane);
;         } else if (it < S6) { const int r = it - S5, kb = r / 16, nb = r % 16; tr_item(wuc, D, nb * 64, kb * 64, nullptr, (bf16*)(ws + WS_UC), 512, nb * 64, scr, lane);
;         } else if (it < S8) { const bool xg = it >= S7; const int r = xg ? it - S7 : it - S6; const int hh = r >> 2, kb = (r >> 1) & 1, nb = r & 1;
;             tr_item((xg ? wrx : wra) + hh * 16384, 128, nb * 64, kb * 64, nullptr, (bf16*)(ws + (xg ? WS_WXT : WS_WAT)) + hh * 16384, 128, nb * 64, scr, lane);
;         } else if (it < S9) { const int r = it - S8, kb = r / 16, nb = r % 16; tr_item(wo, D, nb * 64, kb * 64, nullptr, (bf16*)(ws + WS_WO), D, nb * 64, scr, lane);
;         } else if (it < S10) { const int r = it - S9, kb = r / 16, nb = r % 16; tr_item(wxq, D, nb * 64, kb * 64, gc, (bf16*)(ws + WS_WXQ), D, nb * 64, scr, lane);
.Ltr_go:
	s_cmpk_lt_u32 s0, 1408
	s_cbranch_scc1 .Ltr_seg0
	s_cmpk_lt_u32 s0, 2112
	s_cbranch_scc1 .Ltr_seg1
	s_cmpk_lt_u32 s0, 3136
	s_cbranch_scc1 .Ltr_seg2
	s_cmpk_lt_u32 s0, 3904
	s_cbranch_scc1 .Ltr_seg3
	s_cmpk_lt_u32 s0, 4160
	s_cbranch_scc1 .Ltr_seg4
	s_cmpk_lt_u32 s0, 4288
	s_cbranch_scc1 .Ltr_seg5
	s_cmpk_lt_u32 s0, 4320
	s_cbranch_scc1 .Ltr_seg6
	s_cmpk_lt_u32 s0, 4352
	s_cbranch_scc1 .Ltr_seg7
	s_cmpk_lt_u32 s0, 4608
	s_cbranch_scc1 .Ltr_seg8
	s_cmpk_lt_u32 s0, 4864
	s_cbranch_scc1 .Ltr_seg9
	s_cmpk_lt_u32 s0, 5376
	s_cbranch_scc1 .Ltr_seg10
	s_cmpk_lt_u32 s0, 5632
	s_cbranch_scc1 .Ltr_seg11
	s_cmpk_lt_u32 s0, 7040
	s_cbranch_scc1 .Ltr_seg12
	s_branch .Ltr_seg13

; #define LAS __attribute__((address_space(3)))
; __device__ __forceinline__ void tr_item(const float* W, int ldn, int col0, int k0, const float* g, bf16* WT, int ldk, int drow0, LAS float* scr, int lane) {
;     ...
;     for (int i = 0; i < 16; ++i) { const int kk = 4 * i + kr; f32x4 v = *(const f32x4*)(W + (size_t)(k0 + kk) * ldn + col0 + n4); if (g) v = v * g[k0 + kk];
;         LAS float* d = scr + kk * 65 + n4; d[0] = v.x; d[1] = v.y; d[2] = v.z; d[3] = v.w; }
.Ltr_gdone:
	global_load_dwordx4 v[146:149], v232, s[2:3] nt
	v_add_u32_e32 v232, s38, v232
	global_load_dwordx4 v[150:153], v232, s[2:3] nt
	v_add_u32_e32 v232, s38, v232
	global_load_dwordx4 v[154:157], v232, s[2:3] nt
	v_add_u32_e32 v232, s38, v232
	global_load_dwordx4 v[158:161], v232, s[2:3] nt
	v_add_u32_e32 v232, s38, v232
	global_load_dwordx4 v[162:165], v232, s[2:3] nt
	v_add_u32_e32 v232, s38, v232
	global_load_dwordx4 v[166:169], v232, s[2:3] nt
	v_add_u32_e32 v232, s38, v232
	global_load_dwordx4 v[170:173], v232, s[2:3] nt
	v_add_u32_e32 v232, s38, v232
	global_load_dwordx4 v[174:177], v232, s[2:3] nt
	v_add_u32_e32 v232, s38, v232
	global_load_dwordx4 v[178:181], v232, s[2:3] nt
	v_add_u32_e32 v232, s38, v232
	global_load_dwordx4 v[182:185], v232, s[2:3] nt
	v_add_u32_e32 v232, s38, v232
	global_load_dwordx4 v[186:189], v232, s[2:3] nt
	v_add_u32_e32 v232, s38, v232
	global_load_dwordx4 v[190:193], v232, s[2:3] nt
	v_add_u32_e32 v232, s38, v232
	global_load_dwordx4 v[114:117], v232, s[2:3] nt
	v_add_u32_e32 v232, s38, v232
	global_load_dwordx4 v[118:121], v232, s[2:3] nt
	v_add_u32_e32 v232, s38, v232
	global_load_dwordx4 v[122:125], v232, s[2:3] nt
	v_add_u32_e32 v232, s38, v232
	global_load_dwordx4 v[126:129], v232, s[2:3] nt
	s_waitcnt vmcnt(15)
	v_mul_f32_e32 v146, v210, v146
	v_mul_f32_e32 v147, v210, v147
	v_mul_f32_e32 v148, v210, v148
	v_mul_f32_e32 v149, v210, v149
	ds_write2_b32 v242, v146, v147 offset1:1
	ds_write2_b32 v242, v148, v149 offset0:2 offset1:3
	v_add_u32_e32 v242, 0x410, v242
	s_waitcnt vmcnt(14)
	v_mul_f32_e32 v150, v211, v150
	v_mul_f32_e32 v151, v211, v151
	v_mul_f32_e32 v152, v211, v152
	v_mul_f32_e32 v153, v211, v153
	ds_write2_b32 v242, v150, v151 offset1:1
	ds_write2_b32 v242, v152, v153 offset0:2 offset1:3
	v_add_u32_e32 v242, 0x410, v242
	s_waitcnt vmcnt(13)
	v_mul_f32_e32 v154, v212, v154
	v_mul_f32_e32 v155, v212, v155
	v_mul_f32_e32 v156, v212, v156
	v_mul_f32_e32 v157, v212, v157
	ds_write2_b32 v242, v154, v155 offset1:1
	ds_write2_b32 v242, v156, v157 offset0:2 offset1:3
	v_add_u32_e32 v242, 0x410, v242
	s_waitcnt vmcnt(12)
	v_mul_f32_e32 v158, v213, v158
	v_mul_f32_e32 v159, v213, v159
	v_mul_f32_e32 v160, v213, v160
	v_mul_f32_e32 v161, v213, v161
	ds_write2_b32 v242, v158, v159 offset1:1
	ds_write2_b32 v242, v160, v161 offset0:2 offset1:3
	v_add_u32_e32 v242, 0x410, v242
	s_waitcnt vmcnt(11)
	v_mul_f32_e32 v162, v214, v162
	v_mul_f32_e32 v163, v214, v163
	v_mul_f32_e32 v164, v214, v164
	v_mul_f32_e32 v165, v214, v165
	ds_write2_b32 v242, v162, v163 offset1:1
	ds_write2_b32 v242, v164, v165 offset0:2 offset1:3
	v_add_u32_e32 v242, 0x410, v242
	s_waitcnt vmcnt(10)
	v_mul_f32_e32 v166, v215, v166
	v_mul_f32_e32 v167, v215, v167
	v_mul_f32_e32 v168, v215, v168
	v_mul_f32_e32 v169, v215, v169
	ds_write2_b32 v242, v166, v167 offset1:1
	ds_write2_b32 v242, v168, v169 offset0:2 offset1:3
	v_add_u32_e32 v242, 0x410, v242
	s_waitcnt vmcnt(9)
	v_mul_f32_e32 v170, v216, v170
	v_mul_f32_e32 v171, v216, v171
	v_mul_f32_e32 v172, v216, v172
	v_mul_f32_e32 v173, v216, v173
	ds_write2_b32 v242, v170, v171 offset1:1
	ds_write2_b32 v242, v172, v173 offset0:2 offset1:3
	v_add_u32_e32 v242, 0x410, v242
	s_waitcnt vmcnt(8)
	v_mul_f32_e32 v174, v217, v174
	v_mul_f32_e32 v175, v217, v175
	v_mul_f32_e32 v176, v217, v176
	v_mul_f32_e32 v177, v217, v177
	ds_write2_b32 v242, v174, v175 offset1:1
	ds_write2_b32 v242, v176, v177 offset0:2 offset1:3
	v_add_u32_e32 v242, 0x410, v242
	s_waitcnt vmcnt(7)
	v_mul_f32_e32 v178, v218, v178
	v_mul_f32_e32 v179, v218, v179
	v_mul_f32_e32 v180, v218, v180
	v_mul_f32_e32 v181, v218, v181
	ds_write2_b32 v242, v178, v179 offset1:1
	ds_write2_b32 v242, v180, v181 offset0:2 offset1:3
	v_add_u32_e32 v242, 0x410, v242
	s_waitcnt vmcnt(6)
	v_mul_f32_e32 v182, v219, v182
	v_mul_f32_e32 v183, v219, v183
	v_mul_f32_e32 v184, v219, v184
	v_mul_f32_e32 v185, v219, v185
	ds_write2_b32 v242, v182, v183 offset1:1
	ds_write2_b32 v242, v184, v185 offset0:2 offset1:3
	v_add_u32_e32 v242, 0x410, v242
	s_waitcnt vmcnt(5)
	v_mul_f32_e32 v186, v220, v186
	v_mul_f32_e32 v187, v220, v187
	v_mul_f32_e32 v188, v220, v188
	v_mul_f32_e32 v189, v220, v189
	ds_write2_b32 v242, v186, v187 offset1:1
	ds_write2_b32 v242, v188, v189 offset0:2 offset1:3
	v_add_u32_e32 v242, 0x410, v242
	s_waitcnt vmcnt(4)
	v_mul_f32_e32 v190, v221, v190
	v_mul_f32_e32 v191, v221, v191
	v_mul_f32_e32 v192, v221, v192
	v_mul_f32_e32 v193, v221, v193
	ds_write2_b32 v242, v190, v191 offset1:1
	ds_write2_b32 v242, v192, v193 offset0:2 offset1:3
	v_add_u32_e32 v242, 0x410, v242
	s_waitcnt vmcnt(3)
; #define LAS __attribute__((address_space(3)))
; __device__ __forceinline__ unsigned pk2(float lo, float hi) { return f2bf(lo) | (f2bf(hi) << 16); }
; #define LDS_WAIT() asm volatile("s_waitcnt lgkmcnt(0)" ::: "memory")
; __device__ __forceinline__ void tr_item(const float* W, int ldn, int col0, int k0, const float* g, bf16* WT, int ldk, int drow0, LAS float* scr, int lane) {
;     ...
;     LDS_WAIT(); asm volatile("" ::: "memory");
;     const int c = lane & 7;
; #pragma unroll
;     for (int j = 0; j < 8; ++j) { const int n = (lane >> 3) + 8 * j; const LAS float* s = scr + (8 * c) * 65 + n;
;         v4u o; o.x = pk2(s[0 * 65], s[1 * 65]); o.y = pk2(s[2 * 65], s[3 * 65]); o.z = pk2(s[4 * 65], s[5 * 65]); o.w = pk2(s[6 * 65], s[7 * 65]);
;         *(v4u*)(WT + (size_t)(drow0 + n) * ldk + k0 + 8 * c) = o; }
; __device__ __forceinline__ void phase_prologue(PtrTab TB, unsigned char* ws, float* xout, int l, LAS unsigned char* lds, int gw, int NGW, int lane, int wave) {
;     ...
;     for (int it = gw; it < S14; it += NGW) {
	v_mul_f32_e32 v114, v222, v114
	v_mul_f32_e32 v115, v222, v115
	v_mul_f32_e32 v116, v222, v116
	v_mul_f32_e32 v117, v222, v117
	ds_write2_b32 v242, v114, v115 offset1:1
	ds_write2_b32 v242, v116, v117 offset0:2 offset1:3
	v_add_u32_e32 v242, 0x410, v242
	s_waitcnt vmcnt(2)
	v_mul_f32_e32 v118, v223, v118
	v_mul_f32_e32 v119, v223, v119
	v_mul_f32_e32 v120, v223, v120
	v_mul_f32_e32 v121, v223, v121
	ds_write2_b32 v242, v118, v119 offset1:1
	ds_write2_b32 v242, v120, v121 offset0:2 offset1:3
	v_add_u32_e32 v242, 0x410, v242
	s_waitcnt vmcnt(1)
	v_mul_f32_e32 v122, v230, v122
	v_mul_f32_e32 v123, v230, v123
	v_mul_f32_e32 v124, v230, v124
	v_mul_f32_e32 v125, v230, v125
	ds_write2_b32 v242, v122, v123 offset1:1
	ds_write2_b32 v242, v124, v125 offset0:2 offset1:3
	v_add_u32_e32 v242, 0x410, v242
	s_waitcnt vmcnt(0)
	v_mul_f32_e32 v126, v231, v126
	v_mul_f32_e32 v127, v231, v127
	v_mul_f32_e32 v128, v231, v128
	v_mul_f32_e32 v129, v231, v129
	ds_write2_b32 v242, v126, v127 offset1:1
	ds_write2_b32 v242, v128, v129 offset0:2 offset1:3
	s_waitcnt lgkmcnt(0)
	ds_read2_b32 v[146:147], v62 offset0:0 offset1:65
	ds_read2_b32 v[148:149], v62 offset0:130 offset1:195
	ds_read2_b32 v[150:151], v243 offset0:4 offset1:69
	ds_read2_b32 v[152:153], v243 offset0:134 offset1:199
	ds_read2_b32 v[154:155], v62 offset0:8 offset1:73
	ds_read2_b32 v[156:157], v62 offset0:138 offset1:203
	ds_read2_b32 v[158:159], v243 offset0:12 offset1:77
	ds_read2_b32 v[160:161], v243 offset0:142 offset1:207
	ds_read2_b32 v[162:163], v62 offset0:16 offset1:81
	ds_read2_b32 v[164:165], v62 offset0:146 offset1:211
	ds_read2_b32 v[166:167], v243 offset0:20 offset1:85
	ds_read2_b32 v[168:169], v243 offset0:150 offset1:215
	s_waitcnt lgkmcnt(8)
	v_cvt_pk_bf16_f32 v146, v146, v147
	v_cvt_pk_bf16_f32 v147, v148, v149
	v_cvt_pk_bf16_f32 v148, v150, v151
	v_cvt_pk_bf16_f32 v149, v152, v153
	global_store_dwordx4 v244, v[146:149], s[24:25]
	ds_read2_b32 v[170:171], v62 offset0:24 offset1:89
	ds_read2_b32 v[172:173], v62 offset0:154 offset1:219
	ds_read2_b32 v[174:175], v243 offset0:28 offset1:93
	ds_read2_b32 v[176:177], v243 offset0:158 offset1:223
	s_waitcnt lgkmcnt(8)
	v_cvt_pk_bf16_f32 v154, v154, v155
	v_cvt_pk_bf16_f32 v155, v156, v157
	v_cvt_pk_bf16_f32 v156, v158, v159
	v_cvt_pk_bf16_f32 v157, v160, v161
	global_store_dwordx4 v245, v[154:157], s[24:25]
	ds_read2_b32 v[178:179], v62 offset0:32 offset1:97
	ds_read2_b32 v[180:181], v62 offset0:162 offset1:227
	ds_read2_b32 v[182:183], v243 offset0:36 offset1:101
	ds_read2_b32 v[184:185], v243 offset0:166 offset1:231
	s_waitcnt lgkmcnt(8)
	v_cvt_pk_bf16_f32 v162, v162, v163
	v_cvt_pk_bf16_f32 v163, v164, v165
	v_cvt_pk_bf16_f32 v164, v166, v167
	v_cvt_pk_bf16_f32 v165, v168, v169
	global_store_dwordx4 v246, v[162:165], s[24:25]
	ds_read2_b32 v[186:187], v62 offset0:40 offset1:105
	ds_read2_b32 v[188:189], v62 offset0:170 offset1:235
	ds_read2_b32 v[190:191], v243 offset0:44 offset1:109
	ds_read2_b32 v[192:193], v243 offset0:174 offset1:239
	s_waitcnt lgkmcnt(8)
	v_cvt_pk_bf16_f32 v170, v170, v171
	v_cvt_pk_bf16_f32 v171, v172, v173
	v_cvt_pk_bf16_f32 v172, v174, v175
	v_cvt_pk_bf16_f32 v173, v176, v177
	global_store_dwordx4 v247, v[170:173], s[24:25]
	ds_read2_b32 v[114:115], v62 offset0:48 offset1:113
	ds_read2_b32 v[116:117], v62 offset0:178 offset1:243
	ds_read2_b32 v[118:119], v243 offset0:52 offset1:117
	ds_read2_b32 v[120:121], v243 offset0:182 offset1:247
	s_waitcnt lgkmcnt(8)
	v_cvt_pk_bf16_f32 v178, v178, v179
	v_cvt_pk_bf16_f32 v179, v180, v181
	v_cvt_pk_bf16_f32 v180, v182, v183
	v_cvt_pk_bf16_f32 v181, v184, v185
	global_store_dwordx4 v248, v[178:181], s[24:25]
	ds_read2_b32 v[122:123], v62 offset0:56 offset1:121
	ds_read2_b32 v[124:125], v62 offset0:186 offset1:251
	ds_read2_b32 v[126:127], v243 offset0:60 offset1:125
	ds_read2_b32 v[128:129], v243 offset0:190 offset1:255
	s_waitcnt lgkmcnt(8)
	v_cvt_pk_bf16_f32 v186, v186, v187
	v_cvt_pk_bf16_f32 v187, v188, v189
	v_cvt_pk_bf16_f32 v188, v190, v191
	v_cvt_pk_bf16_f32 v189, v192, v193
	global_store_dwordx4 v249, v[186:189], s[24:25]
	s_waitcnt lgkmcnt(4)
	v_cvt_pk_bf16_f32 v114, v114, v115
	v_cvt_pk_bf16_f32 v115, v116, v117
	v_cvt_pk_bf16_f32 v116, v118, v119
	v_cvt_pk_bf16_f32 v117, v120, v121
	global_store_dwordx4 v250, v[114:117], s[24:25]
	s_waitcnt lgkmcnt(0)
	v_cvt_pk_bf16_f32 v122, v122, v123
	v_cvt_pk_bf16_f32 v123, v124, v125
	v_cvt_pk_bf16_f32 v124, v126, v127
	v_cvt_pk_bf16_f32 v125, v128, v129
	global_store_dwordx4 v251, v[122:125], s[24:25]
	s_cmpk_eq_u32 s8, 0x800
	s_cbranch_scc0 .LBB0_22
	s_addk_i32 s71, 0x800
	s_cmpk_lt_u32 s71, 4992
	s_cbranch_scc1 .LBB0_23
	s_branch .LBB0_214

; __device__ __forceinline__ void phase_prologue(PtrTab TB, unsigned char* ws, float* xout, int l, LAS unsigned char* lds, int gw, int NGW, int lane, int wave) {
;     ...
;     for (int it = gw; it < S14; it += NGW) {
.LBB0_340:
	v_readlane_b32 s0, v254, 58
	v_readlane_b32 s1, v254, 0
	v_readlane_b32 s2, v254, 2
	s_nop 3
	s_cmpk_lg_u32 s1, 0x100
	s_cbranch_scc1 .Lof2_skip
	s_cmpk_lt_u32 s2, 0xa0
	s_cbranch_scc1 .Lof2_skip
	s_cmp_lg_u32 s0, 0
	s_cselect_b32 s15, 1, 0
	s_movk_i32 s14, 0x1040
	s_movk_i32 s12, 0x580
	s_cmovk_i32 s14, 0x1e40
	s_cmovk_i32 s12, 0x1600
	v_lshrrev_b32_e32 v50, 6, v197
	v_and_b32_e32 v49, 63, v197
	s_nop 0
	v_readfirstlane_b32 s3, v50
	s_nop 3
	s_sub_u32 s2, s2, 0xa0
	s_lshl_b32 s2, s2, 3
	s_add_u32 s2, s2, s3
	s_add_u32 s12, s12, s2
	s_mul_i32 s5, s3, 0x4100
	v_and_b32_e32 v40, 15, v49
	v_lshlrev_b32_e32 v40, 2, v40
	v_lshrrev_b32_e32 v41, 4, v49
	v_and_b32_e32 v42, 7, v49
	v_lshlrev_b32_e32 v42, 3, v42
	v_lshrrev_b32_e32 v44, 3, v49
	v_mul_u32_u24_e32 v45, 0x104, v41
	v_lshl_add_u32 v45, v40, 2, v45
	v_add_u32_e32 v45, s5, v45
	v_mul_u32_u24_e32 v48, 0x104, v42
	v_lshl_add_u32 v48, v44, 2, v48
	v_add_u32_e32 v48, s5, v48

; #define g1 (tab_in(TB, 2) + l * D)
; #define w1i (tab_in(TB, 3) + (size_t)l * D * 2 * DFF)
; #define w1o (tab_in(TB, 4) + (size_t)l * DFF * D)
; #define gm (tab_in(TB, 5) + l * D)
; #define win (tab_in(TB, 6) + (size_t)l * D * INW)
; __device__ __forceinline__ void phase_prologue(PtrTab TB, unsigned char* ws, float* xout, int l, LAS unsigned char* lds, int gw, int NGW, int lane, int wave) {
;     ...
;             const bool second = it >= S12; const int r = second ? it - S12 : it; const int kb = r / 88, nb = r % 88; const int n = nb * 64;
;             const int half = n >= DFF ? 1 : 0, nn = n - half * DFF; const int drow = (nn >> 7) * 256 + half * 128 + (nn & 127);
;             tr_item(second ? w2i : w1i, 2 * DFF, n, kb * 64, second ? g2 : g1, (bf16*)(ws + (second ? WS_W2IN : WS_W1IN)), D, drow, scr, lane);
;         } else if (it < S2 || it >= S13) {
;             const bool second = it >= S13; const int r = second ? it - S13 : it - S1; const int kb = r / 16, nb = r % 16;
;             tr_item(second ? w2o : w1o, D, nb * 64, kb * 64, nullptr, (bf16*)(ws + (second ? WS_W2OUT : WS_W1OUT)), DFF, nb * 64, scr, lane);
;         } else if (it < S3) { const int r = it - S2, kb = r / 64, nb = r % 64; tr_item(win, INW, nb * 64, kb * 64, gm, (bf16*)(ws + WS_WIN), D, nb * 64, scr, lane);
.Lof2_norg:
	s_mul_i32 s95, s15, s13
	s_mul_i32 s97, s4, s18
	s_add_u32 s97, s97, s20
	s_lshl_b32 s97, s97, 2
	s_add_u32 s95, s95, s97
	s_lshl_b32 s38, s18, 4
	s_lshl_b32 s44, s32, 4
	s_mul_i32 s24, s9, s32
	s_add_u32 s24, s24, s4
	s_lshl_b32 s24, s24, 1
	s_add_u32 s24, s24, s23
	s_add_u32 s24, s82, s24
	s_addc_u32 s25, s83, 0
	s_lshl_b32 s97, s15, 12
	s_lshl_b32 s1, s4, 2
	s_add_u32 s97, s97, s1
	v_mul_u32_u24_e32 v232, s18, v41
	v_add_lshl_u32 v232, v232, v40, 2
	v_lshlrev_b32_e32 v233, 2, v41
	v_mul_u32_u24_e32 v244, s32, v44
	v_add_lshl_u32 v244, v244, v42, 1
	v_add_u32_e32 v245, s44, v244
	v_add_u32_e32 v246, s44, v245
	v_add_u32_e32 v247, s44, v246
	v_add_u32_e32 v248, s44, v247
	v_add_u32_e32 v249, s44, v248
	v_add_u32_e32 v250, s44, v249
	v_add_u32_e32 v251, s44, v250
	v_mov_b32_e32 v242, v45
	v_add_u32_e32 v243, 0x400, v48
	s_waitcnt lgkmcnt(0)
	s_add_u32 s2, s60, s95
	s_addc_u32 s3, s61, 0
	s_add_u32 s98, s72, s97
	s_addc_u32 s99, s73, 0
	s_bitcmp1_b32 s34, 2
	s_cbranch_scc0 .Lof2_gone
	global_load_dword v210, v233, s[98:99] offset:0
	global_load_dword v211, v233, s[98:99] offset:16
	global_load_dword v212, v233, s[98:99] offset:32
	global_load_dword v213, v233, s[98:99] offset:48
	global_load_dword v214, v233, s[98:99] offset:64
	global_load_dword v215, v233, s[98:99] offset:80
	global_load_dword v216, v233, s[98:99] offset:96
	global_load_dword v217, v233, s[98:99] offset:112
	global_load_dword v218, v233, s[98:99] offset:128
	global_load_dword v219, v233, s[98:99] offset:144
	global_load_dword v220, v233, s[98:99] offset:160
	global_load_dword v221, v233, s[98:99] offset:176
	global_load_dword v222, v233, s[98:99] offset:192
	global_load_dword v223, v233, s[98:99] offset:208
	global_load_dword v230, v233, s[98:99] offset:224
	global_load_dword v231, v233, s[98:99] offset:240
	s_branch .Lof2_gdone

; #define LAS __attribute__((address_space(3)))
; __device__ __forceinline__ void tr_item(const float* W, int ldn, int col0, int k0, const float* g, bf16* WT, int ldk, int drow0, LAS float* scr, int lane) {
;     ...
;     for (int i = 0; i < 16; ++i) { const int kk = 4 * i + kr; f32x4 v = *(const f32x4*)(W + (size_t)(k0 + kk) * ldn + col0 + n4); if (g) v = v * g[k0 + kk];
;         LAS float* d = scr + kk * 65 + n4; d[0] = v.x; d[1] = v.y; d[2] = v.z; d[3] = v.w; }
.Lof2_gdone:
	global_load_dwordx4 v[146:149], v232, s[2:3] nt
	v_add_u32_e32 v232, s38, v232
	global_load_dwordx4 v[150:153], v232, s[2:3] nt
	v_add_u32_e32 v232, s38, v232
	global_load_dwordx4 v[154:157], v232, s[2:3] nt
	v_add_u32_e32 v232, s38, v232
	global_load_dwordx4 v[158:161], v232, s[2:3] nt
	v_add_u32_e32 v232, s38, v232
	global_load_dwordx4 v[166:169], v232, s[2:3] nt
	v_add_u32_e32 v232, s38, v232
	global_load_dwordx4 v[170:173], v232, s[2:3] nt
	v_add_u32_e32 v232, s38, v232
	global_load_dwordx4 v[174:177], v232, s[2:3] nt
	v_add_u32_e32 v232, s38, v232
	global_load_dwordx4 v[178:181], v232, s[2:3] nt
	v_add_u32_e32 v232, s38, v232
	global_load_dwordx4 v[182:185], v232, s[2:3] nt
	v_add_u32_e32 v232, s38, v232
	global_load_dwordx4 v[186:189], v232, s[2:3] nt
	v_add_u32_e32 v232, s38, v232
	global_load_dwordx4 v[190:193], v232, s[2:3] nt
	v_add_u32_e32 v232, s38, v232
	global_load_dwordx4 v[108:111], v232, s[2:3] nt
	v_add_u32_e32 v232, s38, v232
	global_load_dwordx4 v[112:115], v232, s[2:3] nt
	v_add_u32_e32 v232, s38, v232
	global_load_dwordx4 v[116:119], v232, s[2:3] nt
	v_add_u32_e32 v232, s38, v232
	global_load_dwordx4 v[120:123], v232, s[2:3] nt
	v_add_u32_e32 v232, s38, v232
	global_load_dwordx4 v[124:127], v232, s[2:3] nt
	s_waitcnt vmcnt(15)
	v_mul_f32_e32 v146, v210, v146
	v_mul_f32_e32 v147, v210, v147
	v_mul_f32_e32 v148, v210, v148
	v_mul_f32_e32 v149, v210, v149
	ds_write2_b32 v242, v146, v147 offset1:1
	ds_write2_b32 v242, v148, v149 offset0:2 offset1:3
	v_add_u32_e32 v242, 0x410, v242
	s_waitcnt vmcnt(14)
	v_mul_f32_e32 v150, v211, v150
	v_mul_f32_e32 v151, v211, v151
	v_mul_f32_e32 v152, v211, v152
	v_mul_f32_e32 v153, v211, v153
	ds_write2_b32 v242, v150, v151 offset1:1
	ds_write2_b32 v242, v152, v153 offset0:2 offset1:3
	v_add_u32_e32 v242, 0x410, v242
	s_waitcnt vmcnt(13)
	v_mul_f32_e32 v154, v212, v154
	v_mul_f32_e32 v155, v212, v155
	v_mul_f32_e32 v156, v212, v156
	v_mul_f32_e32 v157, v212, v157
	ds_write2_b32 v242, v154, v155 offset1:1
	ds_write2_b32 v242, v156, v157 offset0:2 offset1:3
	v_add_u32_e32 v242, 0x410, v242
	s_waitcnt vmcnt(12)
	v_mul_f32_e32 v158, v213, v158
	v_mul_f32_e32 v159, v213, v159
	v_mul_f32_e32 v160, v213, v160
	v_mul_f32_e32 v161, v213, v161
	ds_write2_b32 v242, v158, v159 offset1:1
	ds_write2_b32 v242, v160, v161 offset0:2 offset1:3
	v_add_u32_e32 v242, 0x410, v242
	s_waitcnt vmcnt(11)
	v_mul_f32_e32 v166, v214, v166
	v_mul_f32_e32 v167, v214, v167
	v_mul_f32_e32 v168, v214, v168
	v_mul_f32_e32 v169, v214, v169
	ds_write2_b32 v242, v166, v167 offset1:1
	ds_write2_b32 v242, v168, v169 offset0:2 offset1:3
	v_add_u32_e32 v242, 0x410, v242
	s_waitcnt vmcnt(10)
	v_mul_f32_e32 v170, v215, v170
	v_mul_f32_e32 v171, v215, v171
	v_mul_f32_e32 v172, v215, v172
	v_mul_f32_e32 v173, v215, v173
	ds_write2_b32 v242, v170, v171 offset1:1
	ds_write2_b32 v242, v172, v173 offset0:2 offset1:3
	v_add_u32_e32 v242, 0x410, v242
	s_waitcnt vmcnt(9)
	v_mul_f32_e32 v174, v216, v174
	v_mul_f32_e32 v175, v216, v175
	v_mul_f32_e32 v176, v216, v176
	v_mul_f32_e32 v177, v216, v177
	ds_write2_b32 v242, v174, v175 offset1:1
	ds_write2_b32 v242, v176, v177 offset0:2 offset1:3
	v_add_u32_e32 v242, 0x410, v242
	s_waitcnt vmcnt(8)
	v_mul_f32_e32 v178, v217, v178
	v_mul_f32_e32 v179, v217, v179
	v_mul_f32_e32 v180, v217, v180
	v_mul_f32_e32 v181, v217, v181
	ds_write2_b32 v242, v178, v179 offset1:1
	ds_write2_b32 v242, v180, v181 offset0:2 offset1:3
	v_add_u32_e32 v242, 0x410, v242
	s_waitcnt vmcnt(7)
	v_mul_f32_e32 v182, v218, v182
	v_mul_f32_e32 v183, v218, v183
	v_mul_f32_e32 v184, v218, v184
	v_mul_f32_e32 v185, v218, v185
	ds_write2_b32 v242, v182, v183 offset1:1
	ds_write2_b32 v242, v184, v185 offset0:2 offset1:3
	v_add_u32_e32 v242, 0x410, v242
	s_waitcnt vmcnt(6)
	v_mul_f32_e32 v186, v219, v186
	v_mul_f32_e32 v187, v219, v187
	v_mul_f32_e32 v188, v219, v188
	v_mul_f32_e32 v189, v219, v189
	ds_write2_b32 v242, v186, v187 offset1:1
	ds_write2_b32 v242, v188, v189 offset0:2 offset1:3
	v_add_u32_e32 v242, 0x410, v242
	s_waitcnt vmcnt(5)
	v_mul_f32_e32 v190, v220, v190
	v_mul_f32_e32 v191, v220, v191
	v_mul_f32_e32 v192, v220, v192
	v_mul_f32_e32 v193, v220, v193
	ds_write2_b32 v242, v190, v191 offset1:1
	ds_write2_b32 v242, v192, v193 offset0:2 offset1:3
	v_add_u32_e32 v242, 0x410, v242
	s_waitcnt vmcnt(4)
	v_mul_f32_e32 v108, v221, v108
	v_mul_f32_e32 v109, v221, v109
	v_mul_f32_e32 v110, v221, v110
	v_mul_f32_e32 v111, v221, v111
	ds_write2_b32 v242, v108, v109 offset1:1
	ds_write2_b32 v242, v110, v111 offset0:2 offset1:3
	v_add_u32_e32 v242, 0x410, v242
	s_waitcnt vmcnt(3)
; #define LAS __attribute__((address_space(3)))
; __device__ __forceinline__ unsigned pk2(float lo, float hi) { return f2bf(lo) | (f2bf(hi) << 16); }
; #define LDS_WAIT() asm volatile("s_waitcnt lgkmcnt(0)" ::: "memory")
; __device__ __forceinline__ void tr_item(const float* W, int ldn, int col0, int k0, const float* g, bf16* WT, int ldk, int drow0, LAS float* scr, int lane) {
;     ...
;     for (int i = 0; i < 16; ++i) { const int kk = 4 * i + kr; f32x4 v = *(const f32x4*)(W + (size_t)(k0 + kk) * ldn + col0 + n4); if (g) v = v * g[k0 + kk];
;         LAS float* d = scr + kk * 65 + n4; d[0] = v.x; d[1] = v.y; d[2] = v.z; d[3] = v.w; }
;     LDS_WAIT(); asm volatile("" ::: "memory");
;     const int c = lane & 7;
; #pragma unroll
;     for (int j = 0; j < 8; ++j) { const int n = (lane >> 3) + 8 * j; const LAS float* s = scr + (8 * c) * 65 + n;
;         v4u o; o.x = pk2(s[0 * 65], s[1 * 65]); o.y = pk2(s[2 * 65], s[3 * 65]); o.z = pk2(s[4 * 65], s[5 * 65]); o.w = pk2(s[6 * 65], s[7 * 65]);
;         *(v4u*)(WT + (size_t)(drow0 + n) * ldk + k0 + 8 * c) = o; }
;     LDS_WAIT(); asm volatile("" ::: "memory");
	v_mul_f32_e32 v112, v222, v112
	v_mul_f32_e32 v113, v222, v113
	v_mul_f32_e32 v114, v222, v114
	v_mul_f32_e32 v115, v222, v115
	ds_write2_b32 v242, v112, v113 offset1:1
	ds_write2_b32 v242, v114, v115 offset0:2 offset1:3
	v_add_u32_e32 v242, 0x410, v242
	s_waitcnt vmcnt(2)
	v_mul_f32_e32 v116, v223, v116
	v_mul_f32_e32 v117, v223, v117
	v_mul_f32_e32 v118, v223, v118
	v_mul_f32_e32 v119, v223, v119
	ds_write2_b32 v242, v116, v117 offset1:1
	ds_write2_b32 v242, v118, v119 offset0:2 offset1:3
	v_add_u32_e32 v242, 0x410, v242
	s_waitcnt vmcnt(1)
	v_mul_f32_e32 v120, v230, v120
	v_mul_f32_e32 v121, v230, v121
	v_mul_f32_e32 v122, v230, v122
	v_mul_f32_e32 v123, v230, v123
	ds_write2_b32 v242, v120, v121 offset1:1
	ds_write2_b32 v242, v122, v123 offset0:2 offset1:3
	v_add_u32_e32 v242, 0x410, v242
	s_waitcnt vmcnt(0)
	v_mul_f32_e32 v124, v231, v124
	v_mul_f32_e32 v125, v231, v125
	v_mul_f32_e32 v126, v231, v126
	v_mul_f32_e32 v127, v231, v127
	ds_write2_b32 v242, v124, v125 offset1:1
	ds_write2_b32 v242, v126, v127 offset0:2 offset1:3
	s_waitcnt lgkmcnt(0)
	ds_read2_b32 v[146:147], v48 offset0:0 offset1:65
	ds_read2_b32 v[148:149], v48 offset0:130 offset1:195
	ds_read2_b32 v[150:151], v243 offset0:4 offset1:69
	ds_read2_b32 v[152:153], v243 offset0:134 offset1:199
	ds_read2_b32 v[154:155], v48 offset0:8 offset1:73
	ds_read2_b32 v[156:157], v48 offset0:138 offset1:203
	ds_read2_b32 v[158:159], v243 offset0:12 offset1:77
	ds_read2_b32 v[160:161], v243 offset0:142 offset1:207
	ds_read2_b32 v[166:167], v48 offset0:16 offset1:81
	ds_read2_b32 v[168:169], v48 offset0:146 offset1:211
	ds_read2_b32 v[170:171], v243 offset0:20 offset1:85
	ds_read2_b32 v[172:173], v243 offset0:150 offset1:215
	s_waitcnt lgkmcnt(8)
	v_cvt_pk_bf16_f32 v146, v146, v147
	v_cvt_pk_bf16_f32 v147, v148, v149
	v_cvt_pk_bf16_f32 v148, v150, v151
	v_cvt_pk_bf16_f32 v149, v152, v153
	global_store_dwordx4 v244, v[146:149], s[24:25]
	ds_read2_b32 v[174:175], v48 offset0:24 offset1:89
	ds_read2_b32 v[176:177], v48 offset0:154 offset1:219
	ds_read2_b32 v[178:179], v243 offset0:28 offset1:93
	ds_read2_b32 v[180:181], v243 offset0:158 offset1:223
	s_waitcnt lgkmcnt(8)
	v_cvt_pk_bf16_f32 v154, v154, v155
	v_cvt_pk_bf16_f32 v155, v156, v157
	v_cvt_pk_bf16_f32 v156, v158, v159
	v_cvt_pk_bf16_f32 v157, v160, v161
	global_store_dwordx4 v245, v[154:157], s[24:25]
	ds_read2_b32 v[182:183], v48 offset0:32 offset1:97
	ds_read2_b32 v[184:185], v48 offset0:162 offset1:227
	ds_read2_b32 v[186:187], v243 offset0:36 offset1:101
	ds_read2_b32 v[188:189], v243 offset0:166 offset1:231
	s_waitcnt lgkmcnt(8)
	v_cvt_pk_bf16_f32 v166, v166, v167
	v_cvt_pk_bf16_f32 v167, v168, v169
	v_cvt_pk_bf16_f32 v168, v170, v171
	v_cvt_pk_bf16_f32 v169, v172, v173
	global_store_dwordx4 v246, v[166:169], s[24:25]
	ds_read2_b32 v[108:109], v48 offset0:40 offset1:105
	ds_read2_b32 v[110:111], v48 offset0:170 offset1:235
	ds_read2_b32 v[112:113], v243 offset0:44 offset1:109
	ds_read2_b32 v[114:115], v243 offset0:174 offset1:239
	s_waitcnt lgkmcnt(8)
	v_cvt_pk_bf16_f32 v174, v174, v175
	v_cvt_pk_bf16_f32 v175, v176, v177
	v_cvt_pk_bf16_f32 v176, v178, v179
	v_cvt_pk_bf16_f32 v177, v180, v181
	global_store_dwordx4 v247, v[174:177], s[24:25]
	ds_read2_b32 v[116:117], v48 offset0:48 offset1:113
	ds_read2_b32 v[118:119], v48 offset0:178 offset1:243
	ds_read2_b32 v[120:121], v243 offset0:52 offset1:117
	ds_read2_b32 v[122:123], v243 offset0:182 offset1:247
	s_waitcnt lgkmcnt(8)
	v_cvt_pk_bf16_f32 v182, v182, v183
	v_cvt_pk_bf16_f32 v183, v184, v185
	v_cvt_pk_bf16_f32 v184, v186, v187
	v_cvt_pk_bf16_f32 v185, v188, v189
	global_store_dwordx4 v248, v[182:185], s[24:25]
	ds_read2_b32 v[124:125], v48 offset0:56 offset1:121
	ds_read2_b32 v[126:127], v48 offset0:186 offset1:251
	ds_read2_b32 v[128:129], v243 offset0:60 offset1:125
	ds_read2_b32 v[130:131], v243 offset0:190 offset1:255
	s_waitcnt lgkmcnt(8)
	v_cvt_pk_bf16_f32 v108, v108, v109
	v_cvt_pk_bf16_f32 v109, v110, v111
	v_cvt_pk_bf16_f32 v110, v112, v113
	v_cvt_pk_bf16_f32 v111, v114, v115
	global_store_dwordx4 v249, v[108:111], s[24:25]
	s_waitcnt lgkmcnt(4)
	v_cvt_pk_bf16_f32 v116, v116, v117
	v_cvt_pk_bf16_f32 v117, v118, v119
	v_cvt_pk_bf16_f32 v118, v120, v121
	v_cvt_pk_bf16_f32 v119, v122, v123
	global_store_dwordx4 v250, v[116:119], s[24:25]
	s_waitcnt lgkmcnt(0)
	v_cvt_pk_bf16_f32 v124, v124, v125
	v_cvt_pk_bf16_f32 v125, v126, v127
	v_cvt_pk_bf16_f32 v126, v128, v129
	v_cvt_pk_bf16_f32 v127, v130, v131
	global_store_dwordx4 v251, v[124:127], s[24:25]
	s_addk_i32 s12, 0x300
	s_cmp_lt_u32 s12, s14
	s_cbranch_scc1 .Lof2_item
